# phase_combine token loop hand-written: all inputs of a token loaded up front with ws-relative addressing, DPP reductions, counted vmcnt per group
# speedup vs baseline: 1.0906x; 1.0192x over previous
; __device__ __forceinline__ void phase_combine(const Params p, int l, char* smem) {
;   char* ws = p.ws;
;   const int lane = ltid() & 63, w = ltid() >> 6;
;   const float lam_init = 0.8f - 0.6f * expf(-0.3f * (float)l);
;   float lam;
;   {
;     const float* lq = (const float*)p.in[I_DLAM] + l * 256;
;     float a = wave_sum(lq[lane] * lq[64 + lane]);
;     float b = wave_sum(lq[128 + lane] * lq[192 + lane]);
;     lam = expf(a) - expf(b) + lam_init;
;   }
;   const float* gng = (const float*)p.in[I_GNG] + l * 512;
;   const float* gnb = (const float*)p.in[I_GNB] + l * 512;
;   const float* subg = (const float*)p.in[I_DSUBG] + l * 128;
;   const u16* P = (const u16*)(ws + OFF_P);
;   const float* YS = (const float*)(ws + OFF_YS);
;   const u16* OB = (const u16*)(ws + OFF_OB);
;   const u16* OB2c = (const u16*)(ws + OFF_OB2);
;   const float* MLp = (const float*)(ws + OFF_ML);
;   u16* YG = (u16*)(ws + OFF_YG);
;   for (int s = lbid() * 4 + w; s < S_; s += gridDim.x * 4) {
.LBB0_53:
	s_andn2_b64 vcc, exec, s[0:1]
	s_cbranch_vccnz .LBB0_248
	v_readlane_b32 s0, v244, 45
	s_cmp_gt_i32 s0, 4
	s_mov_b64 s[0:1], -1
	s_cbranch_scc0 .LBB0_59
	v_readlane_b32 s0, v244, 43
	v_readlane_b32 s1, v244, 44
	s_lshl_b32 s0, s0, 8
	s_waitcnt vmcnt(14)
	v_mov_b32_e32 v0, v171
	s_ashr_i32 s1, s0, 31
	s_lshl_b64 s[0:1], s[0:1], 2
	v_and_b32_e32 v3, 63, v0
	v_mov_b32_e32 v0, v171
	s_add_u32 s0, s14, s0
	s_addc_u32 s1, s15, s1
	v_lshlrev_b32_e32 v168, 2, v3
	v_ashrrev_i32_e32 v1, 6, v0
	global_load_dword v0, v168, s[0:1]
	global_load_dword v2, v168, s[0:1] offset:256
	v_cmp_lt_i32_e32 vcc, v199, v198
	s_mov_b32 s2, s73
	s_waitcnt vmcnt(0)
	v_mul_f32_e32 v4, v0, v2
	v_cndmask_b32_e32 v5, v197, v199, vcc
	v_lshlrev_b32_e32 v5, 2, v5
	ds_bpermute_b32 v4, v5, v4
	v_cmp_lt_i32_e32 vcc, v200, v198
	s_waitcnt lgkmcnt(0)
	v_fmac_f32_e32 v4, v0, v2
	v_cndmask_b32_e32 v0, v197, v200, vcc
	v_lshlrev_b32_e32 v19, 2, v0
	ds_bpermute_b32 v0, v19, v4
	v_cmp_lt_i32_e32 vcc, v201, v198
	s_waitcnt lgkmcnt(0)
	v_add_f32_e32 v0, v4, v0
	v_cndmask_b32_e32 v2, v197, v201, vcc
	v_lshlrev_b32_e32 v21, 2, v2
	ds_bpermute_b32 v2, v21, v0
	v_cmp_lt_i32_e32 vcc, v202, v198
	s_waitcnt lgkmcnt(0)
	v_add_f32_e32 v0, v0, v2
	v_cndmask_b32_e32 v2, v197, v202, vcc
	v_lshlrev_b32_e32 v23, 2, v2
	ds_bpermute_b32 v2, v23, v0
	v_cmp_lt_i32_e32 vcc, v203, v198
	s_waitcnt lgkmcnt(0)
	v_add_f32_e32 v0, v0, v2
	v_cndmask_b32_e32 v2, v197, v203, vcc
	v_lshlrev_b32_e32 v46, 2, v2
	ds_bpermute_b32 v2, v46, v0
	v_cmp_lt_i32_e32 vcc, v204, v198
	s_waitcnt lgkmcnt(0)
	v_add_f32_e32 v2, v0, v2
	v_cndmask_b32_e32 v0, v197, v204, vcc
	v_lshlrev_b32_e32 v47, 2, v0
	global_load_dword v0, v168, s[0:1] offset:512
	global_load_dword v6, v168, s[0:1] offset:768
	ds_bpermute_b32 v4, v47, v2
	s_movk_i32 s0, 0x2000
	s_waitcnt vmcnt(0)
	v_mul_f32_e32 v7, v0, v6
	ds_bpermute_b32 v7, v5, v7
	s_waitcnt lgkmcnt(0)
	v_fmac_f32_e32 v7, v0, v6
	ds_bpermute_b32 v0, v19, v7
	s_waitcnt lgkmcnt(0)
	v_add_f32_e32 v0, v7, v0
	ds_bpermute_b32 v6, v21, v0
	s_waitcnt lgkmcnt(0)
	v_add_f32_e32 v0, v0, v6
	ds_bpermute_b32 v6, v23, v0
	s_waitcnt lgkmcnt(0)
	v_add_f32_e32 v0, v0, v6
	ds_bpermute_b32 v6, v46, v0
	s_waitcnt lgkmcnt(0)
	v_add_f32_e32 v6, v0, v6
	ds_bpermute_b32 v7, v47, v6
	v_lshl_add_u32 v0, s2, 2, v1
	v_cmp_gt_i32_e32 vcc, s0, v0
	s_and_saveexec_b64 s[0:1], vcc
	v_readlane_b32 s30, v247, 35
	v_readlane_b32 s31, v247, 36
	s_movk_i32 s36, 0x1fff
	s_mov_b64 s[38:39], 0x1000000
	s_cbranch_execz .LBB0_58
	v_readlane_b32 s20, v244, 43
	s_mov_b32 s24, s20
	v_cvt_f32_i32_e32 v8, s24
	s_mov_b32 s22, 0x3fb8aa3b
	v_add_f32_e32 v2, v2, v4
	s_mov_b32 s3, 0xc2ce8ed0
	v_mul_f32_e32 v8, 0xbe99999a, v8
	v_mul_f32_e32 v9, 0x3fb8aa3b, v8
	v_fma_f32 v10, v8, s22, -v9
	v_rndne_f32_e32 v11, v9
	v_fmac_f32_e32 v10, 0x32a5705f, v8
	v_sub_f32_e32 v9, v9, v11
	v_add_f32_e32 v9, v9, v10
	v_cvt_i32_f32_e32 v11, v11
	v_exp_f32_e32 v9, v9
	v_mul_f32_e32 v4, 0x3fb8aa3b, v2
	v_cmp_ngt_f32_e32 vcc, s3, v8
	s_mov_b32 s20, 0x42b17218
	v_ldexp_f32 v9, v9, v11
	v_cndmask_b32_e32 v9, 0, v9, vcc
	v_fma_f32 v10, v2, s22, -v4
	v_rndne_f32_e32 v11, v4
	v_cmp_nlt_f32_e32 vcc, s20, v8
	s_waitcnt lgkmcnt(0)
	v_add_f32_e32 v6, v6, v7
	v_fmac_f32_e32 v10, 0x32a5705f, v2
	v_sub_f32_e32 v4, v4, v11
	v_cndmask_b32_e32 v8, v208, v9, vcc
	v_mul_f32_e32 v7, 0x3fb8aa3b, v6
	v_add_f32_e32 v4, v4, v10
	v_cvt_i32_f32_e32 v10, v11
	v_fmamk_f32 v11, v8, 0xbf19999a, v192
	v_fma_f32 v8, v6, s22, -v7
	v_rndne_f32_e32 v9, v7
	v_exp_f32_e32 v4, v4
	v_fmac_f32_e32 v8, 0x32a5705f, v6
	v_sub_f32_e32 v7, v7, v9
	v_add_f32_e32 v7, v7, v8
	v_exp_f32_e32 v7, v7
	v_cvt_i32_f32_e32 v8, v9
	v_ldexp_f32 v4, v4, v10
	v_cmp_ngt_f32_e32 vcc, s3, v2
	v_readlane_b32 s21, v244, 44
	v_lshlrev_b32_e32 v24, 3, v3
	v_cndmask_b32_e32 v4, 0, v4, vcc
	v_cmp_nlt_f32_e32 vcc, s20, v2
	v_mov_b32_e32 v25, v169
	v_lshrrev_b32_e32 v26, 5, v3
	v_cndmask_b32_e32 v2, v208, v4, vcc
	v_ldexp_f32 v4, v7, v8
	v_cmp_ngt_f32_e32 vcc, s3, v6
	v_lshl_or_b32 v26, s2, 5, v26
	v_lshl_add_u64 v[8:9], s[62:63], 0, v[168:169]
	v_cndmask_b32_e32 v4, 0, v4, vcc
	v_cmp_nlt_f32_e32 vcc, s20, v6
	s_lshl_b32 s20, s24, 9
	s_ashr_i32 s21, s20, 31
	s_lshl_b64 s[20:21], s[20:21], 2
	s_add_u32 s22, s10, s20
	s_addc_u32 s23, s11, s21
	s_add_u32 s20, s8, s20
	s_addc_u32 s21, s9, s21
	s_lshl_b32 s24, s24, 7
	s_ashr_i32 s25, s24, 31
	v_cndmask_b32_e32 v4, v208, v4, vcc
	s_lshl_b64 s[24:25], s[24:25], 2
	v_sub_f32_e32 v2, v2, v4
	s_add_u32 s24, s16, s24
	v_lshl_add_u64 v[14:15], s[20:21], 0, v[24:25]
	v_readlane_b32 s20, v247, 37
	v_add_f32_e32 v2, v11, v2
	s_addc_u32 s25, s17, s25
	v_lshlrev_b32_e32 v4, 1, v3
	v_readlane_b32 s21, v247, 38
	v_lshl_add_u64 v[6:7], s[28:29], 0, v[168:169]
	v_sub_f32_e32 v48, 1.0, v11
	v_lshl_add_u64 v[10:11], s[24:25], 0, v[24:25]
	v_lshl_add_u64 v[12:13], s[58:59], 0, v[168:169]
	v_lshl_add_u64 v[16:17], s[22:23], 0, v[24:25]
	v_or_b32_e32 v18, 0x80, v4
	v_or_b32_e32 v20, 0x100, v4
	v_or_b32_e32 v22, 0x180, v4
	v_mov_b32_e32 v3, v2
	v_lshl_add_u64 v[24:25], s[20:21], 0, v[24:25]
	v_lshl_add_u32 v26, v1, 3, v26
	s_mov_b64 s[2:3], 0
	s_cmpk_lg_u32 s72, 0x800
	s_cbranch_scc1 .LBB0_57
	v_lshlrev_b32_e32 v26, 1, v4
	v_lshlrev_b32_e32 v27, 2, v4
	v_lshrrev_b32_e32 v28, 6, v4
	v_lshlrev_b32_e32 v28, 2, v28
	v_mov_b32_e32 v29, v0
	global_load_dwordx2 v[30:31], v[14:15], off
	global_load_dwordx2 v[38:39], v[16:17], off
	global_load_dwordx2 v[32:33], v[14:15], off offset:512
	global_load_dwordx2 v[40:41], v[16:17], off offset:512
	global_load_dwordx2 v[34:35], v[14:15], off offset:1024
	global_load_dwordx2 v[42:43], v[16:17], off offset:1024
	global_load_dwordx2 v[36:37], v[14:15], off offset:1536
	global_load_dwordx2 v[44:45], v[16:17], off offset:1536
	global_load_dwordx2 v[50:51], v[10:11], off
; __device__ __forceinline__ float lo2f(unsigned u) { return __uint_as_float(u << 16); }
; __device__ __forceinline__ float hi2f(unsigned u) { return __uint_as_float(u & 0xffff0000u); }
; __device__ __forceinline__ void phase_combine(const Params p, int l, char* smem) {
;     ...
;   for (int s = lbid() * 4 + w; s < S_; s += gridDim.x * 4) {
;     const u16* grow = P + (size_t)s * NINP + O_G;
; #pragma unroll
;     for (int hp = 0; hp < 4; ++hp) {
;       const int c = hp * 128 + 2 * lane, h = hp * 2 + (lane >> 5);
;       const float2 ya = *(const float2*)(YS + (size_t)s * 512 + c);
;       const float2 yb = *(const float2*)(YS + ((size_t)S_ + s) * 512 + c);
;       float y0 = ya.x + yb.x, y1 = ya.y + yb.y;
;       float sm = y0 + y1;
; #pragma unroll
;       for (int o = 16; o >= 1; o >>= 1) sm += __shfl_xor(sm, o);
;       const float mu = sm * (1.f / 64);
;       const float d0 = y0 - mu, d1 = y1 - mu;
;       float vs = d0 * d0 + d1 * d1;
; #pragma unroll
;       for (int o = 16; o >= 1; o >>= 1) vs += __shfl_xor(vs, o);
;       const float rstd = rsqrtf(vs * (1.f / 64) + 64e-5f);
;       const float2 gg = *(const float2*)(gng + c), gb = *(const float2*)(gnb + c);
;       const float bon = ((const float*)(ws + OFF_BONUS))[s * 8 + h];
;       const float2 vv = *(const float2*)((const float*)(ws + OFF_SCV) + (size_t)s * 512 + c);
;       float o0 = d0 * rstd * gg.x + gb.x + bon * vv.x;
;       float o1 = d1 * rstd * gg.y + gb.y + bon * vv.y;
;       const unsigned gt = *(const unsigned*)(grow + c);
;       const float g0 = lo2f(gt), g1 = hi2f(gt);
;       *(unsigned*)(YG + (size_t)s * 512 + c) = pack2(o0 * g0 * sigmoidf_(g0), o1 * g1 * sigmoidf_(g1));
;     }
.Lcmb_tok:
	v_readfirstlane_b32 s20, v29
	s_nop 3
	s_lshl_b32 s21, s20, 11
	s_add_u32 s22, s21, 0x31480000
	v_add_u32_e32 v176, s22, v27
	v_add_u32_e32 v177, 0x1000000, v176
	s_add_u32 s22, s21, 0x29440000
	v_add_u32_e32 v178, s22, v27
	s_mul_i32 s22, s20, 0x7400
	s_add_u32 s22, s22, 0x16442380
	v_add_u32_e32 v179, s22, v26
	s_lshl_b32 s22, s20, 5
	s_add_u32 s22, s22, 0x31440000
	v_add_u32_e32 v180, s22, v28
	s_lshl_b32 s22, s20, 10
	s_add_u32 s22, s22, 0x3c480000
	v_add_u32_e32 v181, s22, v26
	v_add_u32_e32 v182, 0x800000, v181
	v_add_u32_e32 v183, 0x1000000, v181
	v_add_u32_e32 v184, 0x1800000, v181
	s_lshl_b32 s23, s20, 8
	s_lshl_b32 s24, s20, 3
	global_load_dwordx2 v[52:53], v176, s[96:97]
	global_load_dwordx2 v[54:55], v177, s[96:97]
	global_load_dwordx2 v[56:57], v178, s[96:97]
	global_load_dword v49, v179, s[96:97]
	global_load_dword v58, v180, s[96:97]
	global_load_dwordx2 v[60:61], v176, s[96:97] offset:512
	global_load_dwordx2 v[62:63], v177, s[96:97] offset:512
	global_load_dwordx2 v[66:67], v178, s[96:97] offset:512
	global_load_dword v59, v179, s[96:97] offset:256
	global_load_dword v64, v180, s[96:97] offset:8
	global_load_dwordx2 v[68:69], v176, s[96:97] offset:1024
	global_load_dwordx2 v[70:71], v177, s[96:97] offset:1024
	global_load_dwordx2 v[72:73], v178, s[96:97] offset:1024
	global_load_dword v74, v179, s[96:97] offset:512
	global_load_dword v75, v180, s[96:97] offset:16
	global_load_dwordx2 v[76:77], v176, s[96:97] offset:1536
	global_load_dwordx2 v[78:79], v177, s[96:97] offset:1536
	global_load_dwordx2 v[80:81], v178, s[96:97] offset:1536
	global_load_dword v82, v179, s[96:97] offset:768
	global_load_dword v83, v180, s[96:97] offset:24
	s_add_u32 s22, s23, 0x39c80000
	v_add_u32_e32 v185, s22, v26
	global_load_dword v84, v185, s[96:97]
	global_load_dword v85, v179, s[96:97] offset:3072
	s_add_u32 s22, s23, 0x39e80000
	v_add_u32_e32 v185, s22, v26
	global_load_dword v86, v185, s[96:97]
	global_load_dword v87, v179, s[96:97] offset:3328
	s_add_u32 s22, s23, 0x3a080000
	v_add_u32_e32 v185, s22, v26
	global_load_dword v88, v185, s[96:97]
	global_load_dword v89, v179, s[96:97] offset:3584
	s_add_u32 s22, s23, 0x3a280000
	v_add_u32_e32 v185, s22, v26
	global_load_dword v90, v185, s[96:97]
	global_load_dword v91, v179, s[96:97] offset:3840
	s_add_u32 s22, s24, 0x44483b00
	v_mov_b32_e32 v185, s22
	global_load_dwordx2 v[92:93], v185, s[96:97]
	s_add_u32 s22, s24, 0x44583b00
	v_mov_b32_e32 v185, s22
	global_load_dwordx2 v[94:95], v185, s[96:97]
	s_add_u32 s22, s23, 0x38480000
	v_add_u32_e32 v185, s22, v26
	global_load_dword v96, v185, s[96:97]
	s_add_u32 s22, s23, 0x40483b00
	v_add_u32_e32 v185, s22, v26
	global_load_dword v97, v185, s[96:97]
	s_add_u32 s22, s24, 0x44493b00
	v_mov_b32_e32 v185, s22
	global_load_dwordx2 v[98:99], v185, s[96:97]
	s_add_u32 s22, s24, 0x44593b00
	v_mov_b32_e32 v185, s22
	global_load_dwordx2 v[100:101], v185, s[96:97]
	s_add_u32 s22, s23, 0x38680000
	v_add_u32_e32 v185, s22, v26
	global_load_dword v102, v185, s[96:97]
	s_add_u32 s22, s23, 0x40683b00
	v_add_u32_e32 v185, s22, v26
	global_load_dword v103, v185, s[96:97]
	global_load_dword v104, v179, s[96:97] offset:1024
	s_add_u32 s22, s24, 0x444a3b00
	v_mov_b32_e32 v185, s22
	global_load_dwordx2 v[106:107], v185, s[96:97]
	s_add_u32 s22, s24, 0x445a3b00
	v_mov_b32_e32 v185, s22
	global_load_dwordx2 v[108:109], v185, s[96:97]
	s_add_u32 s22, s23, 0x38880000
	v_add_u32_e32 v185, s22, v26
	global_load_dword v105, v185, s[96:97]
	s_add_u32 s22, s23, 0x40883b00
	v_add_u32_e32 v185, s22, v26
	global_load_dword v110, v185, s[96:97]
	s_add_u32 s22, s24, 0x444b3b00
	v_mov_b32_e32 v185, s22
	global_load_dwordx2 v[112:113], v185, s[96:97]
	s_add_u32 s22, s24, 0x445b3b00
	v_mov_b32_e32 v185, s22
	global_load_dwordx2 v[114:115], v185, s[96:97]
	s_add_u32 s22, s23, 0x38a80000
	v_add_u32_e32 v185, s22, v26
	global_load_dword v111, v185, s[96:97]
	s_add_u32 s22, s23, 0x40a83b00
	v_add_u32_e32 v185, s22, v26
	global_load_dword v116, v185, s[96:97]
	global_load_dword v117, v179, s[96:97] offset:1280
	s_add_u32 s22, s24, 0x444c3b00
	v_mov_b32_e32 v185, s22
	global_load_dwordx2 v[118:119], v185, s[96:97]
	s_add_u32 s22, s24, 0x445c3b00
	v_mov_b32_e32 v185, s22
	global_load_dwordx2 v[120:121], v185, s[96:97]
	s_add_u32 s22, s23, 0x38c80000
	v_add_u32_e32 v185, s22, v26
	global_load_dword v122, v185, s[96:97]
	s_add_u32 s22, s23, 0x40c83b00
	v_add_u32_e32 v185, s22, v26
	global_load_dword v123, v185, s[96:97]
	s_add_u32 s22, s24, 0x444d3b00
	v_mov_b32_e32 v185, s22
	global_load_dwordx2 v[124:125], v185, s[96:97]
	s_add_u32 s22, s24, 0x445d3b00
	v_mov_b32_e32 v185, s22
	global_load_dwordx2 v[126:127], v185, s[96:97]
	s_add_u32 s22, s23, 0x38e80000
	v_add_u32_e32 v185, s22, v26
	global_load_dword v128, v185, s[96:97]
	s_add_u32 s22, s23, 0x40e83b00
	v_add_u32_e32 v185, s22, v26
	global_load_dword v129, v185, s[96:97]
	global_load_dword v130, v179, s[96:97] offset:1536
	s_add_u32 s22, s24, 0x444e3b00
	v_mov_b32_e32 v185, s22
	global_load_dwordx2 v[132:133], v185, s[96:97]
	s_add_u32 s22, s24, 0x445e3b00
	v_mov_b32_e32 v185, s22
	global_load_dwordx2 v[134:135], v185, s[96:97]
	s_add_u32 s22, s23, 0x39080000
	v_add_u32_e32 v185, s22, v26
	global_load_dword v131, v185, s[96:97]
	s_add_u32 s22, s23, 0x41083b00
	v_add_u32_e32 v185, s22, v26
	global_load_dword v136, v185, s[96:97]
	s_add_u32 s22, s24, 0x444f3b00
	v_mov_b32_e32 v185, s22
	global_load_dwordx2 v[138:139], v185, s[96:97]
	s_add_u32 s22, s24, 0x445f3b00
	v_mov_b32_e32 v185, s22
	global_load_dwordx2 v[140:141], v185, s[96:97]
	s_add_u32 s22, s23, 0x39280000
	v_add_u32_e32 v185, s22, v26
	global_load_dword v137, v185, s[96:97]
; __device__ __forceinline__ float lo2f(unsigned u) { return __uint_as_float(u << 16); }
; __device__ __forceinline__ float hi2f(unsigned u) { return __uint_as_float(u & 0xffff0000u); }
; __device__ __forceinline__ void phase_combine(const Params p, int l, char* smem) {
;     ...
;     const u16* grow = P + (size_t)s * NINP + O_G;
; #pragma unroll
;     for (int hp = 0; hp < 4; ++hp) {
;       const int c = hp * 128 + 2 * lane, h = hp * 2 + (lane >> 5);
;       const float2 ya = *(const float2*)(YS + (size_t)s * 512 + c);
;       const float2 yb = *(const float2*)(YS + ((size_t)S_ + s) * 512 + c);
;       float y0 = ya.x + yb.x, y1 = ya.y + yb.y;
;       float sm = y0 + y1;
; #pragma unroll
;       for (int o = 16; o >= 1; o >>= 1) sm += __shfl_xor(sm, o);
;       const float mu = sm * (1.f / 64);
;       const float d0 = y0 - mu, d1 = y1 - mu;
;       float vs = d0 * d0 + d1 * d1;
; #pragma unroll
;       for (int o = 16; o >= 1; o >>= 1) vs += __shfl_xor(vs, o);
;       const float rstd = rsqrtf(vs * (1.f / 64) + 64e-5f);
;       const float2 gg = *(const float2*)(gng + c), gb = *(const float2*)(gnb + c);
;       const float bon = ((const float*)(ws + OFF_BONUS))[s * 8 + h];
;       const float2 vv = *(const float2*)((const float*)(ws + OFF_SCV) + (size_t)s * 512 + c);
;       float o0 = d0 * rstd * gg.x + gb.x + bon * vv.x;
;       float o1 = d1 * rstd * gg.y + gb.y + bon * vv.y;
;       const unsigned gt = *(const unsigned*)(grow + c);
;       const float g0 = lo2f(gt), g1 = hi2f(gt);
;       *(unsigned*)(YG + (size_t)s * 512 + c) = pack2(o0 * g0 * sigmoidf_(g0), o1 * g1 * sigmoidf_(g1));
;     }
	s_add_u32 s22, s23, 0x41283b00
	v_add_u32_e32 v185, s22, v26
	global_load_dword v142, v185, s[96:97]
	global_load_dword v143, v179, s[96:97] offset:1792
	s_add_u32 s22, s24, 0x44503b00
	v_mov_b32_e32 v185, s22
	global_load_dwordx2 v[144:145], v185, s[96:97]
	s_add_u32 s22, s24, 0x44603b00
	v_mov_b32_e32 v185, s22
	global_load_dwordx2 v[146:147], v185, s[96:97]
	s_add_u32 s22, s23, 0x39480000
	v_add_u32_e32 v185, s22, v26
	global_load_dword v148, v185, s[96:97]
	s_add_u32 s22, s23, 0x41483b00
	v_add_u32_e32 v185, s22, v26
	global_load_dword v149, v185, s[96:97]
	global_load_dword v150, v179, s[96:97] offset:2048
	s_add_u32 s22, s24, 0x44513b00
	v_mov_b32_e32 v185, s22
	global_load_dwordx2 v[152:153], v185, s[96:97]
	s_add_u32 s22, s24, 0x44613b00
	v_mov_b32_e32 v185, s22
	global_load_dwordx2 v[154:155], v185, s[96:97]
	s_add_u32 s22, s23, 0x39680000
	v_add_u32_e32 v185, s22, v26
	global_load_dword v151, v185, s[96:97]
	s_add_u32 s22, s23, 0x41683b00
	v_add_u32_e32 v185, s22, v26
	global_load_dword v156, v185, s[96:97]
	global_load_dword v157, v179, s[96:97] offset:2304
	s_add_u32 s22, s24, 0x44523b00
	v_mov_b32_e32 v185, s22
	global_load_dwordx2 v[158:159], v185, s[96:97]
	s_add_u32 s22, s24, 0x44623b00
	v_mov_b32_e32 v185, s22
	global_load_dwordx2 v[160:161], v185, s[96:97]
	s_add_u32 s22, s23, 0x39880000
	v_add_u32_e32 v185, s22, v26
	global_load_dword v162, v185, s[96:97]
	s_add_u32 s22, s23, 0x41883b00
	v_add_u32_e32 v185, s22, v26
	global_load_dword v163, v185, s[96:97]
	global_load_dword v164, v179, s[96:97] offset:2560
	s_add_u32 s22, s24, 0x44533b00
	v_mov_b32_e32 v185, s22
	global_load_dwordx2 v[166:167], v185, s[96:97]
	s_add_u32 s22, s24, 0x44633b00
	v_mov_b32_e32 v185, s22
	global_load_dwordx2 v[172:173], v185, s[96:97]
	s_add_u32 s22, s23, 0x39a80000
	v_add_u32_e32 v185, s22, v26
	global_load_dword v165, v185, s[96:97]
	s_add_u32 s22, s23, 0x41a83b00
	v_add_u32_e32 v185, s22, v26
	global_load_dword v174, v185, s[96:97]
	global_load_dword v175, v179, s[96:97] offset:2816
	s_waitcnt vmcnt(56)
	v_pk_add_f32 v[186:187], v[52:53], v[54:55]
	v_add_f32_e32 v190, v186, v187
	s_nop 1
	v_add_f32_dpp v190, v190, v190 quad_perm:[1,0,3,2] row_mask:0xf bank_mask:0xf bound_ctrl:1
	s_nop 1
	v_add_f32_dpp v190, v190, v190 quad_perm:[2,3,0,1] row_mask:0xf bank_mask:0xf bound_ctrl:1
	s_nop 1
	v_add_f32_dpp v190, v190, v190 row_half_mirror row_mask:0xf bank_mask:0xf bound_ctrl:1
	s_nop 1
	v_add_f32_dpp v190, v190, v190 row_mirror row_mask:0xf bank_mask:0xf bound_ctrl:1
	ds_bpermute_b32 v191, v19, v190
	s_waitcnt lgkmcnt(0)
	v_add_f32_e32 v190, v190, v191
	v_mul_f32_e32 v190, 0x3c800000, v190
	s_nop 0
	v_pk_add_f32 v[188:189], v[186:187], v[190:191] op_sel_hi:[1,0] neg_lo:[0,1] neg_hi:[0,1]
	s_nop 0
	v_pk_mul_f32 v[186:187], v[188:189], v[188:189]
	s_nop 0
	v_add_f32_e32 v190, v186, v187
	s_nop 1
	v_add_f32_dpp v190, v190, v190 quad_perm:[1,0,3,2] row_mask:0xf bank_mask:0xf bound_ctrl:1
	s_nop 1
	v_add_f32_dpp v190, v190, v190 quad_perm:[2,3,0,1] row_mask:0xf bank_mask:0xf bound_ctrl:1
	s_nop 1
	v_add_f32_dpp v190, v190, v190 row_half_mirror row_mask:0xf bank_mask:0xf bound_ctrl:1
	s_nop 1
	v_add_f32_dpp v190, v190, v190 row_mirror row_mask:0xf bank_mask:0xf bound_ctrl:1
	ds_bpermute_b32 v191, v19, v190
	s_waitcnt lgkmcnt(0)
	v_add_f32_e32 v190, v190, v191
	v_fmamk_f32 v190, v190, 0x3c800000, v193
	v_rsq_f32_e32 v190, v190
	s_nop 0
	v_pk_mul_f32 v[188:189], v[188:189], v[190:191] op_sel_hi:[1,0]
	s_nop 0
	v_pk_fma_f32 v[188:189], v[30:31], v[188:189], v[38:39]
	v_mov_b32_e32 v190, v58
	s_nop 0
	v_pk_fma_f32 v[188:189], v[190:191], v[56:57], v[188:189] op_sel_hi:[0,1,1]
	v_lshlrev_b32_e32 v214, 16, v49
	v_and_b32_e32 v215, 0xffff0000, v49
	v_mul_f32_e32 v216, 0xbfb8aa3b, v214
	v_mul_f32_e32 v217, 0xbfb8aa3b, v215
	v_exp_f32_e32 v216, v216
	v_exp_f32_e32 v217, v217
	v_pk_mul_f32 v[188:189], v[188:189], v[214:215]
	v_add_f32_e32 v216, 1.0, v216
	v_add_f32_e32 v217, 1.0, v217
	v_rcp_f32_e32 v216, v216
	v_rcp_f32_e32 v217, v217
	s_nop 0
	v_pk_mul_f32 v[188:189], v[188:189], v[216:217]
	s_nop 0
	v_cvt_pk_bf16_f32 v214, v188, v189
	global_store_dword v181, v214, s[96:97]
	v_pk_add_f32 v[186:187], v[60:61], v[62:63]
	v_add_f32_e32 v190, v186, v187
	s_nop 1
	v_add_f32_dpp v190, v190, v190 quad_perm:[1,0,3,2] row_mask:0xf bank_mask:0xf bound_ctrl:1
	s_nop 1
	v_add_f32_dpp v190, v190, v190 quad_perm:[2,3,0,1] row_mask:0xf bank_mask:0xf bound_ctrl:1
	s_nop 1
	v_add_f32_dpp v190, v190, v190 row_half_mirror row_mask:0xf bank_mask:0xf bound_ctrl:1
	s_nop 1
	v_add_f32_dpp v190, v190, v190 row_mirror row_mask:0xf bank_mask:0xf bound_ctrl:1
	ds_bpermute_b32 v191, v19, v190
	s_waitcnt lgkmcnt(0)
	v_add_f32_e32 v190, v190, v191
	v_mul_f32_e32 v190, 0x3c800000, v190
	s_nop 0
	v_pk_add_f32 v[188:189], v[186:187], v[190:191] op_sel_hi:[1,0] neg_lo:[0,1] neg_hi:[0,1]
	s_nop 0
	v_pk_mul_f32 v[186:187], v[188:189], v[188:189]
	s_nop 0
	v_add_f32_e32 v190, v186, v187
	s_nop 1
	v_add_f32_dpp v190, v190, v190 quad_perm:[1,0,3,2] row_mask:0xf bank_mask:0xf bound_ctrl:1
	s_nop 1
	v_add_f32_dpp v190, v190, v190 quad_perm:[2,3,0,1] row_mask:0xf bank_mask:0xf bound_ctrl:1
	s_nop 1
	v_add_f32_dpp v190, v190, v190 row_half_mirror row_mask:0xf bank_mask:0xf bound_ctrl:1
	s_nop 1
	v_add_f32_dpp v190, v190, v190 row_mirror row_mask:0xf bank_mask:0xf bound_ctrl:1
	ds_bpermute_b32 v191, v19, v190
	s_waitcnt lgkmcnt(0)
; __device__ __forceinline__ float lo2f(unsigned u) { return __uint_as_float(u << 16); }
; __device__ __forceinline__ float hi2f(unsigned u) { return __uint_as_float(u & 0xffff0000u); }
; __device__ __forceinline__ void phase_combine(const Params p, int l, char* smem) {
;     ...
;       const float2 ya = *(const float2*)(YS + (size_t)s * 512 + c);
;       const float2 yb = *(const float2*)(YS + ((size_t)S_ + s) * 512 + c);
;       float y0 = ya.x + yb.x, y1 = ya.y + yb.y;
;       float sm = y0 + y1;
; #pragma unroll
;       for (int o = 16; o >= 1; o >>= 1) sm += __shfl_xor(sm, o);
;       const float mu = sm * (1.f / 64);
;       const float d0 = y0 - mu, d1 = y1 - mu;
;       float vs = d0 * d0 + d1 * d1;
; #pragma unroll
;       for (int o = 16; o >= 1; o >>= 1) vs += __shfl_xor(vs, o);
;       const float rstd = rsqrtf(vs * (1.f / 64) + 64e-5f);
;       const float2 gg = *(const float2*)(gng + c), gb = *(const float2*)(gnb + c);
;       const float bon = ((const float*)(ws + OFF_BONUS))[s * 8 + h];
;       const float2 vv = *(const float2*)((const float*)(ws + OFF_SCV) + (size_t)s * 512 + c);
;       float o0 = d0 * rstd * gg.x + gb.x + bon * vv.x;
;       float o1 = d1 * rstd * gg.y + gb.y + bon * vv.y;
;       const unsigned gt = *(const unsigned*)(grow + c);
;       const float g0 = lo2f(gt), g1 = hi2f(gt);
;       *(unsigned*)(YG + (size_t)s * 512 + c) = pack2(o0 * g0 * sigmoidf_(g0), o1 * g1 * sigmoidf_(g1));
;     }
;     ...
;         if (br == 2) {
;           MERGE_LOAD(8 + h, oa, ob)
;         } else {
;           const unsigned o = *(const unsigned*)(OB + ((size_t)(12 + h) * S_ + s) * 128 + 2 * lane);
;           oa = lo2f(o);
;           ob = hi2f(o);
;         }
;         const unsigned gg = *(const unsigned*)(grow + br * 512 + h * 128 + 2 * lane);
;         float g0 = lo2f(gg), g1 = hi2f(gg);
;         u16* dst = YG + ((size_t)br * S_ + s) * 512 + h * 128;
;         *(unsigned*)(dst + 2 * lane) = pack2(oa * g0 * sigmoidf_(g0), ob * g1 * sigmoidf_(g1));
	v_add_f32_e32 v190, v190, v191
	v_fmamk_f32 v190, v190, 0x3c800000, v193
	v_rsq_f32_e32 v190, v190
	s_nop 0
	v_pk_mul_f32 v[188:189], v[188:189], v[190:191] op_sel_hi:[1,0]
	s_nop 0
	v_pk_fma_f32 v[188:189], v[32:33], v[188:189], v[40:41]
	v_mov_b32_e32 v190, v64
	s_nop 0
	v_pk_fma_f32 v[188:189], v[190:191], v[66:67], v[188:189] op_sel_hi:[0,1,1]
	v_lshlrev_b32_e32 v214, 16, v59
	v_and_b32_e32 v215, 0xffff0000, v59
	v_mul_f32_e32 v216, 0xbfb8aa3b, v214
	v_mul_f32_e32 v217, 0xbfb8aa3b, v215
	v_exp_f32_e32 v216, v216
	v_exp_f32_e32 v217, v217
	v_pk_mul_f32 v[188:189], v[188:189], v[214:215]
	v_add_f32_e32 v216, 1.0, v216
	v_add_f32_e32 v217, 1.0, v217
	v_rcp_f32_e32 v216, v216
	v_rcp_f32_e32 v217, v217
	s_nop 0
	v_pk_mul_f32 v[188:189], v[188:189], v[216:217]
	s_nop 0
	v_cvt_pk_bf16_f32 v214, v188, v189
	global_store_dword v181, v214, s[96:97] offset:256
	v_pk_add_f32 v[186:187], v[68:69], v[70:71]
	v_add_f32_e32 v190, v186, v187
	s_nop 1
	v_add_f32_dpp v190, v190, v190 quad_perm:[1,0,3,2] row_mask:0xf bank_mask:0xf bound_ctrl:1
	s_nop 1
	v_add_f32_dpp v190, v190, v190 quad_perm:[2,3,0,1] row_mask:0xf bank_mask:0xf bound_ctrl:1
	s_nop 1
	v_add_f32_dpp v190, v190, v190 row_half_mirror row_mask:0xf bank_mask:0xf bound_ctrl:1
	s_nop 1
	v_add_f32_dpp v190, v190, v190 row_mirror row_mask:0xf bank_mask:0xf bound_ctrl:1
	ds_bpermute_b32 v191, v19, v190
	s_waitcnt lgkmcnt(0)
	v_add_f32_e32 v190, v190, v191
	v_mul_f32_e32 v190, 0x3c800000, v190
	s_nop 0
	v_pk_add_f32 v[188:189], v[186:187], v[190:191] op_sel_hi:[1,0] neg_lo:[0,1] neg_hi:[0,1]
	s_nop 0
	v_pk_mul_f32 v[186:187], v[188:189], v[188:189]
	s_nop 0
	v_add_f32_e32 v190, v186, v187
	s_nop 1
	v_add_f32_dpp v190, v190, v190 quad_perm:[1,0,3,2] row_mask:0xf bank_mask:0xf bound_ctrl:1
	s_nop 1
	v_add_f32_dpp v190, v190, v190 quad_perm:[2,3,0,1] row_mask:0xf bank_mask:0xf bound_ctrl:1
	s_nop 1
	v_add_f32_dpp v190, v190, v190 row_half_mirror row_mask:0xf bank_mask:0xf bound_ctrl:1
	s_nop 1
	v_add_f32_dpp v190, v190, v190 row_mirror row_mask:0xf bank_mask:0xf bound_ctrl:1
	ds_bpermute_b32 v191, v19, v190
	s_waitcnt lgkmcnt(0)
	v_add_f32_e32 v190, v190, v191
	v_fmamk_f32 v190, v190, 0x3c800000, v193
	v_rsq_f32_e32 v190, v190
	s_nop 0
	v_pk_mul_f32 v[188:189], v[188:189], v[190:191] op_sel_hi:[1,0]
	s_nop 0
	v_pk_fma_f32 v[188:189], v[34:35], v[188:189], v[42:43]
	v_mov_b32_e32 v190, v75
	s_nop 0
	v_pk_fma_f32 v[188:189], v[190:191], v[72:73], v[188:189] op_sel_hi:[0,1,1]
	v_lshlrev_b32_e32 v214, 16, v74
	v_and_b32_e32 v215, 0xffff0000, v74
	v_mul_f32_e32 v216, 0xbfb8aa3b, v214
	v_mul_f32_e32 v217, 0xbfb8aa3b, v215
	v_exp_f32_e32 v216, v216
	v_exp_f32_e32 v217, v217
	v_pk_mul_f32 v[188:189], v[188:189], v[214:215]
	v_add_f32_e32 v216, 1.0, v216
	v_add_f32_e32 v217, 1.0, v217
	v_rcp_f32_e32 v216, v216
	v_rcp_f32_e32 v217, v217
	s_nop 0
	v_pk_mul_f32 v[188:189], v[188:189], v[216:217]
	s_nop 0
	v_cvt_pk_bf16_f32 v214, v188, v189
	global_store_dword v181, v214, s[96:97] offset:512
	v_pk_add_f32 v[186:187], v[76:77], v[78:79]
	v_add_f32_e32 v190, v186, v187
	s_nop 1
	v_add_f32_dpp v190, v190, v190 quad_perm:[1,0,3,2] row_mask:0xf bank_mask:0xf bound_ctrl:1
	s_nop 1
	v_add_f32_dpp v190, v190, v190 quad_perm:[2,3,0,1] row_mask:0xf bank_mask:0xf bound_ctrl:1
	s_nop 1
	v_add_f32_dpp v190, v190, v190 row_half_mirror row_mask:0xf bank_mask:0xf bound_ctrl:1
	s_nop 1
	v_add_f32_dpp v190, v190, v190 row_mirror row_mask:0xf bank_mask:0xf bound_ctrl:1
	ds_bpermute_b32 v191, v19, v190
	s_waitcnt lgkmcnt(0)
	v_add_f32_e32 v190, v190, v191
	v_mul_f32_e32 v190, 0x3c800000, v190
	s_nop 0
	v_pk_add_f32 v[188:189], v[186:187], v[190:191] op_sel_hi:[1,0] neg_lo:[0,1] neg_hi:[0,1]
	s_nop 0
	v_pk_mul_f32 v[186:187], v[188:189], v[188:189]
	s_nop 0
	v_add_f32_e32 v190, v186, v187
	s_nop 1
	v_add_f32_dpp v190, v190, v190 quad_perm:[1,0,3,2] row_mask:0xf bank_mask:0xf bound_ctrl:1
	s_nop 1
	v_add_f32_dpp v190, v190, v190 quad_perm:[2,3,0,1] row_mask:0xf bank_mask:0xf bound_ctrl:1
	s_nop 1
	v_add_f32_dpp v190, v190, v190 row_half_mirror row_mask:0xf bank_mask:0xf bound_ctrl:1
	s_nop 1
	v_add_f32_dpp v190, v190, v190 row_mirror row_mask:0xf bank_mask:0xf bound_ctrl:1
	ds_bpermute_b32 v191, v19, v190
	s_waitcnt lgkmcnt(0)
	v_add_f32_e32 v190, v190, v191
	v_fmamk_f32 v190, v190, 0x3c800000, v193
	v_rsq_f32_e32 v190, v190
	s_nop 0
	v_pk_mul_f32 v[188:189], v[188:189], v[190:191] op_sel_hi:[1,0]
	s_nop 0
	v_pk_fma_f32 v[188:189], v[36:37], v[188:189], v[44:45]
	v_mov_b32_e32 v190, v83
	s_nop 0
	v_pk_fma_f32 v[188:189], v[190:191], v[80:81], v[188:189] op_sel_hi:[0,1,1]
	v_lshlrev_b32_e32 v214, 16, v82
	v_and_b32_e32 v215, 0xffff0000, v82
	v_mul_f32_e32 v216, 0xbfb8aa3b, v214
	v_mul_f32_e32 v217, 0xbfb8aa3b, v215
	v_exp_f32_e32 v216, v216
	v_exp_f32_e32 v217, v217
	v_pk_mul_f32 v[188:189], v[188:189], v[214:215]
	v_add_f32_e32 v216, 1.0, v216
	v_add_f32_e32 v217, 1.0, v217
	v_rcp_f32_e32 v216, v216
	v_rcp_f32_e32 v217, v217
	s_nop 0
	v_pk_mul_f32 v[188:189], v[188:189], v[216:217]
	s_nop 0
	v_cvt_pk_bf16_f32 v214, v188, v189
	global_store_dword v181, v214, s[96:97] offset:768
	v_lshlrev_b32_e32 v186, 16, v84
	v_and_b32_e32 v187, 0xffff0000, v84
	v_lshlrev_b32_e32 v214, 16, v85
	v_and_b32_e32 v215, 0xffff0000, v85
	v_mul_f32_e32 v216, 0xbfb8aa3b, v214
	v_mul_f32_e32 v217, 0xbfb8aa3b, v215
	v_exp_f32_e32 v216, v216
	v_exp_f32_e32 v217, v217
	v_pk_mul_f32 v[186:187], v[186:187], v[214:215]
	v_add_f32_e32 v216, 1.0, v216
	v_add_f32_e32 v217, 1.0, v217
	v_rcp_f32_e32 v216, v216
	v_rcp_f32_e32 v217, v217
	s_nop 0
	v_pk_mul_f32 v[186:187], v[186:187], v[216:217]
	s_nop 0
	v_cvt_pk_bf16_f32 v214, v186, v187
	global_store_dword v184, v214, s[96:97]
; __device__ __forceinline__ float lo2f(unsigned u) { return __uint_as_float(u << 16); }
; __device__ __forceinline__ float hi2f(unsigned u) { return __uint_as_float(u & 0xffff0000u); }
; __device__ __forceinline__ void phase_combine(const Params p, int l, char* smem) {
;     ...
; #pragma unroll
;     for (int h = 0; h < 4; ++h) {
;       float a1, b1, a2, b2;
;       MERGE_LOAD(h * 2, a1, b1)
;       MERGE_LOAD(h * 2 + 1, a2, b2)
;       float a = a1 - lam * a2, b = b1 - lam * b2;
;       float ss = wave_sum(a * a + b * b);
;       float rs = rsqrtf(ss * (1.f / 128) + 1e-6f) * (1.f - lam_init);
;       const unsigned gg = *(const unsigned*)(grow + 512 + h * 128 + 2 * lane);
;       float g0 = lo2f(gg), g1 = hi2f(gg);
;       const float2 sg = *(const float2*)(subg + 2 * lane);
;       u16* dst = YG + ((size_t)S_ + s) * 512 + h * 128;
;       *(unsigned*)(dst + 2 * lane) = pack2(a * rs * sg.x * g0 * sigmoidf_(g0), b * rs * sg.y * g1 * sigmoidf_(g1));
;     }
;     ...
;         if (br == 2) {
;           MERGE_LOAD(8 + h, oa, ob)
;         } else {
;           const unsigned o = *(const unsigned*)(OB + ((size_t)(12 + h) * S_ + s) * 128 + 2 * lane);
;           oa = lo2f(o);
;           ob = hi2f(o);
;         }
;         const unsigned gg = *(const unsigned*)(grow + br * 512 + h * 128 + 2 * lane);
;         float g0 = lo2f(gg), g1 = hi2f(gg);
;         u16* dst = YG + ((size_t)br * S_ + s) * 512 + h * 128;
;         *(unsigned*)(dst + 2 * lane) = pack2(oa * g0 * sigmoidf_(g0), ob * g1 * sigmoidf_(g1));
	v_lshlrev_b32_e32 v186, 16, v86
	v_and_b32_e32 v187, 0xffff0000, v86
	v_lshlrev_b32_e32 v214, 16, v87
	v_and_b32_e32 v215, 0xffff0000, v87
	v_mul_f32_e32 v216, 0xbfb8aa3b, v214
	v_mul_f32_e32 v217, 0xbfb8aa3b, v215
	v_exp_f32_e32 v216, v216
	v_exp_f32_e32 v217, v217
	v_pk_mul_f32 v[186:187], v[186:187], v[214:215]
	v_add_f32_e32 v216, 1.0, v216
	v_add_f32_e32 v217, 1.0, v217
	v_rcp_f32_e32 v216, v216
	v_rcp_f32_e32 v217, v217
	s_nop 0
	v_pk_mul_f32 v[186:187], v[186:187], v[216:217]
	s_nop 0
	v_cvt_pk_bf16_f32 v214, v186, v187
	global_store_dword v184, v214, s[96:97] offset:256
	v_lshlrev_b32_e32 v186, 16, v88
	v_and_b32_e32 v187, 0xffff0000, v88
	v_lshlrev_b32_e32 v214, 16, v89
	v_and_b32_e32 v215, 0xffff0000, v89
	v_mul_f32_e32 v216, 0xbfb8aa3b, v214
	v_mul_f32_e32 v217, 0xbfb8aa3b, v215
	v_exp_f32_e32 v216, v216
	v_exp_f32_e32 v217, v217
	v_pk_mul_f32 v[186:187], v[186:187], v[214:215]
	v_add_f32_e32 v216, 1.0, v216
	v_add_f32_e32 v217, 1.0, v217
	v_rcp_f32_e32 v216, v216
	v_rcp_f32_e32 v217, v217
	s_nop 0
	v_pk_mul_f32 v[186:187], v[186:187], v[216:217]
	s_nop 0
	v_cvt_pk_bf16_f32 v214, v186, v187
	global_store_dword v184, v214, s[96:97] offset:512
	v_lshlrev_b32_e32 v186, 16, v90
	v_and_b32_e32 v187, 0xffff0000, v90
	v_lshlrev_b32_e32 v214, 16, v91
	v_and_b32_e32 v215, 0xffff0000, v91
	v_mul_f32_e32 v216, 0xbfb8aa3b, v214
	v_mul_f32_e32 v217, 0xbfb8aa3b, v215
	v_exp_f32_e32 v216, v216
	v_exp_f32_e32 v217, v217
	v_pk_mul_f32 v[186:187], v[186:187], v[214:215]
	v_add_f32_e32 v216, 1.0, v216
	v_add_f32_e32 v217, 1.0, v217
	v_rcp_f32_e32 v216, v216
	v_rcp_f32_e32 v217, v217
	s_nop 0
	v_pk_mul_f32 v[186:187], v[186:187], v[216:217]
	s_nop 0
	v_cvt_pk_bf16_f32 v214, v186, v187
	global_store_dword v184, v214, s[96:97] offset:768
	s_waitcnt vmcnt(28)
	v_max_f32_e32 v218, v92, v94
	v_sub_f32_e32 v219, v94, v218
	v_sub_f32_e32 v218, v92, v218
	v_exp_f32_e32 v218, v218
	v_exp_f32_e32 v219, v219
	v_lshlrev_b32_e32 v220, 16, v96
	v_and_b32_e32 v221, 0xffff0000, v96
	v_lshlrev_b32_e32 v222, 16, v97
	v_and_b32_e32 v223, 0xffff0000, v97
	v_mul_f32_e32 v186, v218, v93
	v_fmac_f32_e32 v186, v219, v95
	v_rcp_f32_e32 v187, v186
	v_pk_mul_f32 v[220:221], v[218:219], v[220:221] op_sel_hi:[0,1]
	v_pk_mul_f32 v[222:223], v[218:219], v[222:223] op_sel:[1,0] op_sel_hi:[1,1]
	v_pk_add_f32 v[220:221], v[220:221], v[222:223]
	v_mov_b32_e32 v218, v187
	s_nop 0
	v_pk_mul_f32 v[186:187], v[218:219], v[220:221] op_sel_hi:[0,1]
	v_max_f32_e32 v218, v98, v100
	v_sub_f32_e32 v219, v100, v218
	v_sub_f32_e32 v218, v98, v218
	v_exp_f32_e32 v218, v218
	v_exp_f32_e32 v219, v219
	v_lshlrev_b32_e32 v220, 16, v102
	v_and_b32_e32 v221, 0xffff0000, v102
	v_lshlrev_b32_e32 v222, 16, v103
	v_and_b32_e32 v223, 0xffff0000, v103
	v_mul_f32_e32 v188, v218, v99
	v_fmac_f32_e32 v188, v219, v101
	v_rcp_f32_e32 v189, v188
	v_pk_mul_f32 v[220:221], v[218:219], v[220:221] op_sel_hi:[0,1]
	v_pk_mul_f32 v[222:223], v[218:219], v[222:223] op_sel:[1,0] op_sel_hi:[1,1]
	v_pk_add_f32 v[220:221], v[220:221], v[222:223]
	v_mov_b32_e32 v218, v189
	s_nop 0
	v_pk_mul_f32 v[188:189], v[218:219], v[220:221] op_sel_hi:[0,1]
	v_pk_fma_f32 v[186:187], v[188:189], v[2:3], v[186:187] op_sel_hi:[1,0,1] neg_lo:[0,1,0] neg_hi:[0,1,0]
	s_nop 0
	v_pk_mul_f32 v[188:189], v[186:187], v[186:187]
	s_nop 0
	v_add_f32_e32 v190, v188, v189
	s_nop 1
	v_add_f32_dpp v190, v190, v190 quad_perm:[1,0,3,2] row_mask:0xf bank_mask:0xf bound_ctrl:1
	s_nop 1
	v_add_f32_dpp v190, v190, v190 quad_perm:[2,3,0,1] row_mask:0xf bank_mask:0xf bound_ctrl:1
	s_nop 1
	v_add_f32_dpp v190, v190, v190 row_half_mirror row_mask:0xf bank_mask:0xf bound_ctrl:1
	s_nop 1
	v_add_f32_dpp v190, v190, v190 row_mirror row_mask:0xf bank_mask:0xf bound_ctrl:1
	ds_bpermute_b32 v191, v19, v190
	s_waitcnt lgkmcnt(0)
	v_add_f32_e32 v190, v190, v191
	ds_bpermute_b32 v191, v5, v190
	s_waitcnt lgkmcnt(0)
	v_add_f32_e32 v190, v190, v191
	v_fmamk_f32 v190, v190, 0x3c000000, v170
	v_rsq_f32_e32 v190, v190
	s_nop 0
	v_mul_f32_e32 v190, v190, v48
	s_nop 0
	v_pk_mul_f32 v[186:187], v[186:187], v[190:191] op_sel_hi:[1,0]
	s_nop 0
	v_pk_mul_f32 v[186:187], v[186:187], v[50:51]
	v_lshlrev_b32_e32 v214, 16, v104
	v_and_b32_e32 v215, 0xffff0000, v104
	v_mul_f32_e32 v216, 0xbfb8aa3b, v214
	v_mul_f32_e32 v217, 0xbfb8aa3b, v215
	v_exp_f32_e32 v216, v216
	v_exp_f32_e32 v217, v217
	v_pk_mul_f32 v[186:187], v[186:187], v[214:215]
	v_add_f32_e32 v216, 1.0, v216
	v_add_f32_e32 v217, 1.0, v217
	v_rcp_f32_e32 v216, v216
	v_rcp_f32_e32 v217, v217
	s_nop 0
	v_pk_mul_f32 v[186:187], v[186:187], v[216:217]
	s_nop 0
	v_cvt_pk_bf16_f32 v214, v186, v187
	global_store_dword v182, v214, s[96:97]
	v_max_f32_e32 v218, v106, v108
	v_sub_f32_e32 v219, v108, v218
	v_sub_f32_e32 v218, v106, v218
	v_exp_f32_e32 v218, v218
	v_exp_f32_e32 v219, v219
	v_lshlrev_b32_e32 v220, 16, v105
	v_and_b32_e32 v221, 0xffff0000, v105
	v_lshlrev_b32_e32 v222, 16, v110
	v_and_b32_e32 v223, 0xffff0000, v110
	v_mul_f32_e32 v186, v218, v107
	v_fmac_f32_e32 v186, v219, v109
	v_rcp_f32_e32 v187, v186
	v_pk_mul_f32 v[220:221], v[218:219], v[220:221] op_sel_hi:[0,1]
	v_pk_mul_f32 v[222:223], v[218:219], v[222:223] op_sel:[1,0] op_sel_hi:[1,1]
	v_pk_add_f32 v[220:221], v[220:221], v[222:223]
	v_mov_b32_e32 v218, v187
	s_nop 0
	v_pk_mul_f32 v[186:187], v[218:219], v[220:221] op_sel_hi:[0,1]
	v_max_f32_e32 v218, v112, v114
	v_sub_f32_e32 v219, v114, v218
	v_sub_f32_e32 v218, v112, v218
	v_exp_f32_e32 v218, v218
	v_exp_f32_e32 v219, v219
	v_lshlrev_b32_e32 v220, 16, v111
	v_and_b32_e32 v221, 0xffff0000, v111
	v_lshlrev_b32_e32 v222, 16, v116
	v_and_b32_e32 v223, 0xffff0000, v116
	v_mul_f32_e32 v188, v218, v113
	v_fmac_f32_e32 v188, v219, v115
	v_rcp_f32_e32 v189, v188
	v_pk_mul_f32 v[220:221], v[218:219], v[220:221] op_sel_hi:[0,1]
	v_pk_mul_f32 v[222:223], v[218:219], v[222:223] op_sel:[1,0] op_sel_hi:[1,1]
	v_pk_add_f32 v[220:221], v[220:221], v[222:223]
	v_mov_b32_e32 v218, v189
	s_nop 0
	v_pk_mul_f32 v[188:189], v[218:219], v[220:221] op_sel_hi:[0,1]
	v_pk_fma_f32 v[186:187], v[188:189], v[2:3], v[186:187] op_sel_hi:[1,0,1] neg_lo:[0,1,0] neg_hi:[0,1,0]
	s_nop 0
	v_pk_mul_f32 v[188:189], v[186:187], v[186:187]
	s_nop 0
	v_add_f32_e32 v190, v188, v189
	s_nop 1
	v_add_f32_dpp v190, v190, v190 quad_perm:[1,0,3,2] row_mask:0xf bank_mask:0xf bound_ctrl:1
	s_nop 1
	v_add_f32_dpp v190, v190, v190 quad_perm:[2,3,0,1] row_mask:0xf bank_mask:0xf bound_ctrl:1
	s_nop 1
	v_add_f32_dpp v190, v190, v190 row_half_mirror row_mask:0xf bank_mask:0xf bound_ctrl:1
	s_nop 1
	v_add_f32_dpp v190, v190, v190 row_mirror row_mask:0xf bank_mask:0xf bound_ctrl:1
	ds_bpermute_b32 v191, v19, v190
	s_waitcnt lgkmcnt(0)
; __device__ __forceinline__ float lo2f(unsigned u) { return __uint_as_float(u << 16); }
; __device__ __forceinline__ float hi2f(unsigned u) { return __uint_as_float(u & 0xffff0000u); }
; __device__ __forceinline__ void phase_combine(const Params p, int l, char* smem) {
;     ...
; #pragma unroll
;     for (int h = 0; h < 4; ++h) {
;       float a1, b1, a2, b2;
;       MERGE_LOAD(h * 2, a1, b1)
;       MERGE_LOAD(h * 2 + 1, a2, b2)
;       float a = a1 - lam * a2, b = b1 - lam * b2;
;       float ss = wave_sum(a * a + b * b);
;       float rs = rsqrtf(ss * (1.f / 128) + 1e-6f) * (1.f - lam_init);
;       const unsigned gg = *(const unsigned*)(grow + 512 + h * 128 + 2 * lane);
;       float g0 = lo2f(gg), g1 = hi2f(gg);
;       const float2 sg = *(const float2*)(subg + 2 * lane);
;       u16* dst = YG + ((size_t)S_ + s) * 512 + h * 128;
;       *(unsigned*)(dst + 2 * lane) = pack2(a * rs * sg.x * g0 * sigmoidf_(g0), b * rs * sg.y * g1 * sigmoidf_(g1));
;     }
	v_add_f32_e32 v190, v190, v191
	ds_bpermute_b32 v191, v5, v190
	s_waitcnt lgkmcnt(0)
	v_add_f32_e32 v190, v190, v191
	v_fmamk_f32 v190, v190, 0x3c000000, v170
	v_rsq_f32_e32 v190, v190
	s_nop 0
	v_mul_f32_e32 v190, v190, v48
	s_nop 0
	v_pk_mul_f32 v[186:187], v[186:187], v[190:191] op_sel_hi:[1,0]
	s_nop 0
	v_pk_mul_f32 v[186:187], v[186:187], v[50:51]
	v_lshlrev_b32_e32 v214, 16, v117
	v_and_b32_e32 v215, 0xffff0000, v117
	v_mul_f32_e32 v216, 0xbfb8aa3b, v214
	v_mul_f32_e32 v217, 0xbfb8aa3b, v215
	v_exp_f32_e32 v216, v216
	v_exp_f32_e32 v217, v217
	v_pk_mul_f32 v[186:187], v[186:187], v[214:215]
	v_add_f32_e32 v216, 1.0, v216
	v_add_f32_e32 v217, 1.0, v217
	v_rcp_f32_e32 v216, v216
	v_rcp_f32_e32 v217, v217
	s_nop 0
	v_pk_mul_f32 v[186:187], v[186:187], v[216:217]
	s_nop 0
	v_cvt_pk_bf16_f32 v214, v186, v187
	global_store_dword v182, v214, s[96:97] offset:256
	v_max_f32_e32 v218, v118, v120
	v_sub_f32_e32 v219, v120, v218
	v_sub_f32_e32 v218, v118, v218
	v_exp_f32_e32 v218, v218
	v_exp_f32_e32 v219, v219
	v_lshlrev_b32_e32 v220, 16, v122
	v_and_b32_e32 v221, 0xffff0000, v122
	v_lshlrev_b32_e32 v222, 16, v123
	v_and_b32_e32 v223, 0xffff0000, v123
	v_mul_f32_e32 v186, v218, v119
	v_fmac_f32_e32 v186, v219, v121
	v_rcp_f32_e32 v187, v186
	v_pk_mul_f32 v[220:221], v[218:219], v[220:221] op_sel_hi:[0,1]
	v_pk_mul_f32 v[222:223], v[218:219], v[222:223] op_sel:[1,0] op_sel_hi:[1,1]
	v_pk_add_f32 v[220:221], v[220:221], v[222:223]
	v_mov_b32_e32 v218, v187
	s_nop 0
	v_pk_mul_f32 v[186:187], v[218:219], v[220:221] op_sel_hi:[0,1]
	v_max_f32_e32 v218, v124, v126
	v_sub_f32_e32 v219, v126, v218
	v_sub_f32_e32 v218, v124, v218
	v_exp_f32_e32 v218, v218
	v_exp_f32_e32 v219, v219
	v_lshlrev_b32_e32 v220, 16, v128
	v_and_b32_e32 v221, 0xffff0000, v128
	v_lshlrev_b32_e32 v222, 16, v129
	v_and_b32_e32 v223, 0xffff0000, v129
	v_mul_f32_e32 v188, v218, v125
	v_fmac_f32_e32 v188, v219, v127
	v_rcp_f32_e32 v189, v188
	v_pk_mul_f32 v[220:221], v[218:219], v[220:221] op_sel_hi:[0,1]
	v_pk_mul_f32 v[222:223], v[218:219], v[222:223] op_sel:[1,0] op_sel_hi:[1,1]
	v_pk_add_f32 v[220:221], v[220:221], v[222:223]
	v_mov_b32_e32 v218, v189
	s_nop 0
	v_pk_mul_f32 v[188:189], v[218:219], v[220:221] op_sel_hi:[0,1]
	v_pk_fma_f32 v[186:187], v[188:189], v[2:3], v[186:187] op_sel_hi:[1,0,1] neg_lo:[0,1,0] neg_hi:[0,1,0]
	s_nop 0
	v_pk_mul_f32 v[188:189], v[186:187], v[186:187]
	s_nop 0
	v_add_f32_e32 v190, v188, v189
	s_nop 1
	v_add_f32_dpp v190, v190, v190 quad_perm:[1,0,3,2] row_mask:0xf bank_mask:0xf bound_ctrl:1
	s_nop 1
	v_add_f32_dpp v190, v190, v190 quad_perm:[2,3,0,1] row_mask:0xf bank_mask:0xf bound_ctrl:1
	s_nop 1
	v_add_f32_dpp v190, v190, v190 row_half_mirror row_mask:0xf bank_mask:0xf bound_ctrl:1
	s_nop 1
	v_add_f32_dpp v190, v190, v190 row_mirror row_mask:0xf bank_mask:0xf bound_ctrl:1
	ds_bpermute_b32 v191, v19, v190
	s_waitcnt lgkmcnt(0)
	v_add_f32_e32 v190, v190, v191
	ds_bpermute_b32 v191, v5, v190
	s_waitcnt lgkmcnt(0)
	v_add_f32_e32 v190, v190, v191
	v_fmamk_f32 v190, v190, 0x3c000000, v170
	v_rsq_f32_e32 v190, v190
	s_nop 0
	v_mul_f32_e32 v190, v190, v48
	s_nop 0
	v_pk_mul_f32 v[186:187], v[186:187], v[190:191] op_sel_hi:[1,0]
	s_nop 0
	v_pk_mul_f32 v[186:187], v[186:187], v[50:51]
	v_lshlrev_b32_e32 v214, 16, v130
	v_and_b32_e32 v215, 0xffff0000, v130
	v_mul_f32_e32 v216, 0xbfb8aa3b, v214
	v_mul_f32_e32 v217, 0xbfb8aa3b, v215
	v_exp_f32_e32 v216, v216
	v_exp_f32_e32 v217, v217
	v_pk_mul_f32 v[186:187], v[186:187], v[214:215]
	v_add_f32_e32 v216, 1.0, v216
	v_add_f32_e32 v217, 1.0, v217
	v_rcp_f32_e32 v216, v216
	v_rcp_f32_e32 v217, v217
	s_nop 0
	v_pk_mul_f32 v[186:187], v[186:187], v[216:217]
	s_nop 0
	v_cvt_pk_bf16_f32 v214, v186, v187
	global_store_dword v182, v214, s[96:97] offset:512
	v_max_f32_e32 v218, v132, v134
	v_sub_f32_e32 v219, v134, v218
	v_sub_f32_e32 v218, v132, v218
	v_exp_f32_e32 v218, v218
	v_exp_f32_e32 v219, v219
	v_lshlrev_b32_e32 v220, 16, v131
	v_and_b32_e32 v221, 0xffff0000, v131
	v_lshlrev_b32_e32 v222, 16, v136
	v_and_b32_e32 v223, 0xffff0000, v136
	v_mul_f32_e32 v186, v218, v133
	v_fmac_f32_e32 v186, v219, v135
	v_rcp_f32_e32 v187, v186
	v_pk_mul_f32 v[220:221], v[218:219], v[220:221] op_sel_hi:[0,1]
	v_pk_mul_f32 v[222:223], v[218:219], v[222:223] op_sel:[1,0] op_sel_hi:[1,1]
	v_pk_add_f32 v[220:221], v[220:221], v[222:223]
	v_mov_b32_e32 v218, v187
	s_nop 0
	v_pk_mul_f32 v[186:187], v[218:219], v[220:221] op_sel_hi:[0,1]
	v_max_f32_e32 v218, v138, v140
	v_sub_f32_e32 v219, v140, v218
	v_sub_f32_e32 v218, v138, v218
	v_exp_f32_e32 v218, v218
	v_exp_f32_e32 v219, v219
	v_lshlrev_b32_e32 v220, 16, v137
	v_and_b32_e32 v221, 0xffff0000, v137
	v_lshlrev_b32_e32 v222, 16, v142
	v_and_b32_e32 v223, 0xffff0000, v142
	v_mul_f32_e32 v188, v218, v139
	v_fmac_f32_e32 v188, v219, v141
	v_rcp_f32_e32 v189, v188
	v_pk_mul_f32 v[220:221], v[218:219], v[220:221] op_sel_hi:[0,1]
	v_pk_mul_f32 v[222:223], v[218:219], v[222:223] op_sel:[1,0] op_sel_hi:[1,1]
	v_pk_add_f32 v[220:221], v[220:221], v[222:223]
	v_mov_b32_e32 v218, v189
	s_nop 0
	v_pk_mul_f32 v[188:189], v[218:219], v[220:221] op_sel_hi:[0,1]
	v_pk_fma_f32 v[186:187], v[188:189], v[2:3], v[186:187] op_sel_hi:[1,0,1] neg_lo:[0,1,0] neg_hi:[0,1,0]
	s_nop 0
	v_pk_mul_f32 v[188:189], v[186:187], v[186:187]
	s_nop 0
	v_add_f32_e32 v190, v188, v189
	s_nop 1
	v_add_f32_dpp v190, v190, v190 quad_perm:[1,0,3,2] row_mask:0xf bank_mask:0xf bound_ctrl:1
	s_nop 1
	v_add_f32_dpp v190, v190, v190 quad_perm:[2,3,0,1] row_mask:0xf bank_mask:0xf bound_ctrl:1
	s_nop 1
	v_add_f32_dpp v190, v190, v190 row_half_mirror row_mask:0xf bank_mask:0xf bound_ctrl:1
	s_nop 1
	v_add_f32_dpp v190, v190, v190 row_mirror row_mask:0xf bank_mask:0xf bound_ctrl:1
	ds_bpermute_b32 v191, v19, v190
	s_waitcnt lgkmcnt(0)
; __device__ __forceinline__ float lo2f(unsigned u) { return __uint_as_float(u << 16); }
; __device__ __forceinline__ float hi2f(unsigned u) { return __uint_as_float(u & 0xffff0000u); }
; __device__ __forceinline__ void phase_combine(const Params p, int l, char* smem) {
;     ...
; #pragma unroll
;     for (int br = 2; br < 4; ++br) {
; #pragma unroll
;       for (int h = 0; h < 4; ++h) {
;         float oa, ob;
;         if (br == 2) {
;           MERGE_LOAD(8 + h, oa, ob)
;         } else {
;           const unsigned o = *(const unsigned*)(OB + ((size_t)(12 + h) * S_ + s) * 128 + 2 * lane);
;           oa = lo2f(o);
;           ob = hi2f(o);
;         }
;         const unsigned gg = *(const unsigned*)(grow + br * 512 + h * 128 + 2 * lane);
;         float g0 = lo2f(gg), g1 = hi2f(gg);
;         u16* dst = YG + ((size_t)br * S_ + s) * 512 + h * 128;
;         *(unsigned*)(dst + 2 * lane) = pack2(oa * g0 * sigmoidf_(g0), ob * g1 * sigmoidf_(g1));
;       }
;     }
;     ...
;   }
	v_add_f32_e32 v190, v190, v191
	ds_bpermute_b32 v191, v5, v190
	s_waitcnt lgkmcnt(0)
	v_add_f32_e32 v190, v190, v191
	v_fmamk_f32 v190, v190, 0x3c000000, v170
	v_rsq_f32_e32 v190, v190
	s_nop 0
	v_mul_f32_e32 v190, v190, v48
	s_nop 0
	v_pk_mul_f32 v[186:187], v[186:187], v[190:191] op_sel_hi:[1,0]
	s_nop 0
	v_pk_mul_f32 v[186:187], v[186:187], v[50:51]
	v_lshlrev_b32_e32 v214, 16, v143
	v_and_b32_e32 v215, 0xffff0000, v143
	v_mul_f32_e32 v216, 0xbfb8aa3b, v214
	v_mul_f32_e32 v217, 0xbfb8aa3b, v215
	v_exp_f32_e32 v216, v216
	v_exp_f32_e32 v217, v217
	v_pk_mul_f32 v[186:187], v[186:187], v[214:215]
	v_add_f32_e32 v216, 1.0, v216
	v_add_f32_e32 v217, 1.0, v217
	v_rcp_f32_e32 v216, v216
	v_rcp_f32_e32 v217, v217
	s_nop 0
	v_pk_mul_f32 v[186:187], v[186:187], v[216:217]
	s_nop 0
	v_cvt_pk_bf16_f32 v214, v186, v187
	global_store_dword v182, v214, s[96:97] offset:768
	s_waitcnt vmcnt(12)
	v_max_f32_e32 v218, v144, v146
	v_sub_f32_e32 v219, v146, v218
	v_sub_f32_e32 v218, v144, v218
	v_exp_f32_e32 v218, v218
	v_exp_f32_e32 v219, v219
	v_lshlrev_b32_e32 v220, 16, v148
	v_and_b32_e32 v221, 0xffff0000, v148
	v_lshlrev_b32_e32 v222, 16, v149
	v_and_b32_e32 v223, 0xffff0000, v149
	v_mul_f32_e32 v186, v218, v145
	v_fmac_f32_e32 v186, v219, v147
	v_rcp_f32_e32 v187, v186
	v_pk_mul_f32 v[220:221], v[218:219], v[220:221] op_sel_hi:[0,1]
	v_pk_mul_f32 v[222:223], v[218:219], v[222:223] op_sel:[1,0] op_sel_hi:[1,1]
	v_pk_add_f32 v[220:221], v[220:221], v[222:223]
	v_mov_b32_e32 v218, v187
	s_nop 0
	v_pk_mul_f32 v[186:187], v[218:219], v[220:221] op_sel_hi:[0,1]
	v_lshlrev_b32_e32 v214, 16, v150
	v_and_b32_e32 v215, 0xffff0000, v150
	v_mul_f32_e32 v216, 0xbfb8aa3b, v214
	v_mul_f32_e32 v217, 0xbfb8aa3b, v215
	v_exp_f32_e32 v216, v216
	v_exp_f32_e32 v217, v217
	v_pk_mul_f32 v[186:187], v[186:187], v[214:215]
	v_add_f32_e32 v216, 1.0, v216
	v_add_f32_e32 v217, 1.0, v217
	v_rcp_f32_e32 v216, v216
	v_rcp_f32_e32 v217, v217
	s_nop 0
	v_pk_mul_f32 v[186:187], v[186:187], v[216:217]
	s_nop 0
	v_cvt_pk_bf16_f32 v214, v186, v187
	global_store_dword v183, v214, s[96:97]
	v_max_f32_e32 v218, v152, v154
	v_sub_f32_e32 v219, v154, v218
	v_sub_f32_e32 v218, v152, v218
	v_exp_f32_e32 v218, v218
	v_exp_f32_e32 v219, v219
	v_lshlrev_b32_e32 v220, 16, v151
	v_and_b32_e32 v221, 0xffff0000, v151
	v_lshlrev_b32_e32 v222, 16, v156
	v_and_b32_e32 v223, 0xffff0000, v156
	v_mul_f32_e32 v186, v218, v153
	v_fmac_f32_e32 v186, v219, v155
	v_rcp_f32_e32 v187, v186
	v_pk_mul_f32 v[220:221], v[218:219], v[220:221] op_sel_hi:[0,1]
	v_pk_mul_f32 v[222:223], v[218:219], v[222:223] op_sel:[1,0] op_sel_hi:[1,1]
	v_pk_add_f32 v[220:221], v[220:221], v[222:223]
	v_mov_b32_e32 v218, v187
	s_nop 0
	v_pk_mul_f32 v[186:187], v[218:219], v[220:221] op_sel_hi:[0,1]
	v_lshlrev_b32_e32 v214, 16, v157
	v_and_b32_e32 v215, 0xffff0000, v157
	v_mul_f32_e32 v216, 0xbfb8aa3b, v214
	v_mul_f32_e32 v217, 0xbfb8aa3b, v215
	v_exp_f32_e32 v216, v216
	v_exp_f32_e32 v217, v217
	v_pk_mul_f32 v[186:187], v[186:187], v[214:215]
	v_add_f32_e32 v216, 1.0, v216
	v_add_f32_e32 v217, 1.0, v217
	v_rcp_f32_e32 v216, v216
	v_rcp_f32_e32 v217, v217
	s_nop 0
	v_pk_mul_f32 v[186:187], v[186:187], v[216:217]
	s_nop 0
	v_cvt_pk_bf16_f32 v214, v186, v187
	global_store_dword v183, v214, s[96:97] offset:256
	v_max_f32_e32 v218, v158, v160
	v_sub_f32_e32 v219, v160, v218
	v_sub_f32_e32 v218, v158, v218
	v_exp_f32_e32 v218, v218
	v_exp_f32_e32 v219, v219
	v_lshlrev_b32_e32 v220, 16, v162
	v_and_b32_e32 v221, 0xffff0000, v162
	v_lshlrev_b32_e32 v222, 16, v163
	v_and_b32_e32 v223, 0xffff0000, v163
	v_mul_f32_e32 v186, v218, v159
	v_fmac_f32_e32 v186, v219, v161
	v_rcp_f32_e32 v187, v186
	v_pk_mul_f32 v[220:221], v[218:219], v[220:221] op_sel_hi:[0,1]
	v_pk_mul_f32 v[222:223], v[218:219], v[222:223] op_sel:[1,0] op_sel_hi:[1,1]
	v_pk_add_f32 v[220:221], v[220:221], v[222:223]
	v_mov_b32_e32 v218, v187
	s_nop 0
	v_pk_mul_f32 v[186:187], v[218:219], v[220:221] op_sel_hi:[0,1]
	v_lshlrev_b32_e32 v214, 16, v164
	v_and_b32_e32 v215, 0xffff0000, v164
	v_mul_f32_e32 v216, 0xbfb8aa3b, v214
	v_mul_f32_e32 v217, 0xbfb8aa3b, v215
	v_exp_f32_e32 v216, v216
	v_exp_f32_e32 v217, v217
	v_pk_mul_f32 v[186:187], v[186:187], v[214:215]
	v_add_f32_e32 v216, 1.0, v216
	v_add_f32_e32 v217, 1.0, v217
	v_rcp_f32_e32 v216, v216
	v_rcp_f32_e32 v217, v217
	s_nop 0
	v_pk_mul_f32 v[186:187], v[186:187], v[216:217]
	s_nop 0
	v_cvt_pk_bf16_f32 v214, v186, v187
	global_store_dword v183, v214, s[96:97] offset:512
	v_max_f32_e32 v218, v166, v172
	v_sub_f32_e32 v219, v172, v218
	v_sub_f32_e32 v218, v166, v218
	v_exp_f32_e32 v218, v218
	v_exp_f32_e32 v219, v219
	v_lshlrev_b32_e32 v220, 16, v165
	v_and_b32_e32 v221, 0xffff0000, v165
	v_lshlrev_b32_e32 v222, 16, v174
	v_and_b32_e32 v223, 0xffff0000, v174
	v_mul_f32_e32 v186, v218, v167
	v_fmac_f32_e32 v186, v219, v173
	v_rcp_f32_e32 v187, v186
	v_pk_mul_f32 v[220:221], v[218:219], v[220:221] op_sel_hi:[0,1]
	v_pk_mul_f32 v[222:223], v[218:219], v[222:223] op_sel:[1,0] op_sel_hi:[1,1]
	v_pk_add_f32 v[220:221], v[220:221], v[222:223]
	v_mov_b32_e32 v218, v187
	s_nop 0
	v_pk_mul_f32 v[186:187], v[218:219], v[220:221] op_sel_hi:[0,1]
	v_lshlrev_b32_e32 v214, 16, v175
	v_and_b32_e32 v215, 0xffff0000, v175
	v_mul_f32_e32 v216, 0xbfb8aa3b, v214
	v_mul_f32_e32 v217, 0xbfb8aa3b, v215
	v_exp_f32_e32 v216, v216
	v_exp_f32_e32 v217, v217
	v_pk_mul_f32 v[186:187], v[186:187], v[214:215]
	v_add_f32_e32 v216, 1.0, v216
	v_add_f32_e32 v217, 1.0, v217
	v_rcp_f32_e32 v216, v216
	v_rcp_f32_e32 v217, v217
	s_nop 0
	v_pk_mul_f32 v[186:187], v[186:187], v[216:217]
	s_nop 0
	v_cvt_pk_bf16_f32 v214, v186, v187
	global_store_dword v183, v214, s[96:97] offset:768
	v_add_u32_e32 v29, s72, v29
	v_cmp_gt_i32_e32 vcc, 0x2000, v29
	s_cbranch_vccnz .Lcmb_tok
	s_branch .LBB0_58

; __device__ __forceinline__ unsigned xb_ld(unsigned* p)              { return __hip_atomic_load(p, __ATOMIC_RELAXED, __HIP_MEMORY_SCOPE_AGENT); }
; __global__ void __launch_bounds__(256, 2) mega(Params p, int ph_lo, int ph_hi) {
;     ...
;   for (int ph = ph_lo; ph < ph_hi; ++ph) {
;     if (ph == 0) {
;       if (PH_MASK & 1) phase_w(p, smem);
;     } else {
;       int l = (ph - 1) / 9, sp = (ph - 1) % 9;
;       switch (sp) {
;         case 0: if (PH_MASK & 2) phase_gemm_in(p, l, smem, VB);
;           if (DUP_MASK & 1) { __syncthreads(); phase_gemm_in(p, l, smem, VB); }
;           break;
;         case 1: if (PH_MASK & 4) phase_prep<false>(p, l, smem);
;           if (DUP_MASK & 256) { __syncthreads(); phase_prep<true>(p, l, smem); }
;           break;
;         case 2: if (PH_MASK & 8) phase_gemm_mla(p, l, smem, VB);
;           if (DUP_MASK & 16) { __syncthreads(); phase_gemm_mla(p, l, smem, VB); }
;           break;
;         case 3: if (PH_MASK & 16) phase_mla_post(p, l, smem);
;           if (DUP_MASK & 32) { __syncthreads(); phase_mla_post(p, l, smem); }
;           break;
;         case 4: if (PH_MASK & 32) phase_attn_scan<AT_MASK>(p, l, smem); break;
;         case 5: if (PH_MASK & 64) phase_combine(p, l, smem);
;           if (DUP_MASK & 64) { __syncthreads(); phase_combine(p, l, smem); }
;           break;
;         case 6: if (PH_MASK & 128) phase_gemm_branch(p, l, smem, VB);
;           if (DUP_MASK & 4) { __syncthreads(); phase_gemm_branch(p, l, smem, VB); }
;           break;
;         case 7: if (PH_MASK & 256) phase_gemm_out(p, l, smem, VB); break;
;         case 8:
;           if (l + 1 < L_) rms_rows<true>((const float*)p.out, S_, (const float*)p.in[I_NORMG] + (l + 1) * D_, (u16*)(p.ws + OFF_H));
;           if ((DUP_MASK & 128) && l + 1 < L_) rms_rows<true>((const float*)p.out, S_, (const float*)p.in[I_NORMG] + (l + 1) * D_, (u16*)(p.ws + OFF_H));
;           break;
;       }
;     }
;     ...
;     if (ph + 1 < ph_hi) {
;       if (ph == ph_lo) {
;         if (ph_hi < 0) grid.sync();
;         xcd_barrier(xb);
;         if (threadIdx.x == 0 && gridDim.x == 512) {
;           bool ok = true;
;           for (int j = 0; j < 8; ++j) ok = ok && (xb_ld((unsigned*)(p.ws + OFF_BAR) + 8 * j) == 64u);
;           if (ok && xb.x < 8u) s_vbid = s_cand;
;         }
;         __syncthreads();
;       } else xcd_barrier(xb);
;     }
;   }
.Ltramp_10:
	s_branch .LBB0_10
.Ltramp_11:
	s_branch .LBB0_11
.Ltramp_12:
	s_branch .LBB0_12
